# low-rank epilogue: decay via sigmoid identity, hoisted invariant loads
# speedup vs baseline: 1.0273x; 1.0273x over previous
.LBB0_950:
	s_and_b64 vcc, exec, s[8:9]
	s_cbranch_vccz .LBB0_953
	v_or_b32_e32 v0, s54, v157
	v_or_b32_e32 v1, s35, v157
	v_lshlrev_b32_e32 v64, 7, v0
	v_lshl_add_u64 v[16:17], v[70:71], 0, v[64:65]
	v_lshlrev_b32_e32 v64, 7, v1
	v_lshl_add_u64 v[28:29], v[72:73], 0, v[64:65]
	v_add_co_u32_e32 v8, vcc, 0x3000, v28
	s_nop 1
	v_addc_co_u32_e32 v9, vcc, 0, v29, vcc
	v_add_co_u32_e32 v4, vcc, s20, v16
	s_nop 1
	v_addc_co_u32_e32 v5, vcc, 0, v17, vcc
	v_add_co_u32_e32 v12, vcc, s21, v16
	global_load_dwordx4 v[0:3], v[4:5], off offset:-4096
	s_nop 0
	global_load_dwordx4 v[4:7], v[4:5], off
	v_addc_co_u32_e32 v13, vcc, 0, v17, vcc
	global_load_dwordx4 v[8:11], v[8:9], off
	s_nop 0
	global_load_dwordx4 v[12:15], v[12:13], off
	s_nop 0
	global_load_dwordx4 v[16:19], v[16:17], off
	s_nop 0
	global_load_dwordx4 v[20:23], v[28:29], off
	v_add_co_u32_e32 v24, vcc, s19, v28
	s_nop 1
	v_addc_co_u32_e32 v25, vcc, 0, v29, vcc
	global_load_dwordx4 v[24:27], v[24:25], off
	v_add_co_u32_e32 v28, vcc, s20, v28
	s_nop 1
	v_addc_co_u32_e32 v29, vcc, 0, v29, vcc
	global_load_dwordx4 v[28:31], v[28:29], off
	s_barrier
	s_waitcnt vmcnt(3)
	ds_write_b128 v85, v[16:19]
	s_waitcnt vmcnt(2)
	ds_write_b128 v85, v[20:23] offset:18432
	s_waitcnt vmcnt(1)
	ds_write_b128 v85, v[24:27] offset:23040
	ds_write_b128 v85, v[8:11] offset:32256
	ds_write_b128 v85, v[0:3] offset:4608
	ds_write_b128 v85, v[4:7] offset:9216
	ds_write_b128 v85, v[12:15] offset:13824
	s_waitcnt vmcnt(0)
	ds_write_b128 v85, v[28:31] offset:27648
	s_waitcnt lgkmcnt(0)
	s_barrier
	ds_read_b128 v[0:3], v86 offset:4608
	ds_read_b128 v[4:7], v87 offset:23040
	ds_read_b128 v[8:11], v86
	ds_read_b128 v[100:103], v86 offset:32
	ds_read_b128 v[12:15], v87 offset:18432
	ds_read_b128 v[104:107], v87 offset:18464
	ds_read_b128 v[108:111], v86 offset:4640
	ds_read_b128 v[112:115], v87 offset:23072
	s_waitcnt lgkmcnt(5)
	v_mfma_f32_32x32x16_bf16 v[32:47], v[4:7], v[8:11], 0
	s_lshl_b32 s8, s16, 10
	v_readlane_b32 s72, v253, 42
	s_or_b32 s8, s17, s8
	v_readlane_b32 s80, v253, 50
	v_readlane_b32 s81, v253, 51
	v_readlane_b32 s73, v253, 43
	v_readlane_b32 s74, v253, 44
	s_waitcnt lgkmcnt(3)
	v_mfma_f32_32x32x16_bf16 v[48:63], v[12:15], v[8:11], 0
	v_readlane_b32 s75, v253, 45
	v_readlane_b32 s76, v253, 46
	v_readlane_b32 s77, v253, 47
	v_readlane_b32 s78, v253, 48
	v_readlane_b32 s79, v253, 49
	v_readlane_b32 s82, v253, 52
	v_readlane_b32 s83, v253, 53
	v_mfma_f32_32x32x16_bf16 v[16:31], v[12:15], v[0:3], 0
	v_readlane_b32 s84, v253, 54
	v_readlane_b32 s85, v253, 55
	v_readlane_b32 s86, v253, 56
	v_readlane_b32 s87, v253, 57
	v_mfma_f32_32x32x16_bf16 v[0:15], v[4:7], v[0:3], 0
	s_waitcnt lgkmcnt(2)
	v_mfma_f32_32x32x16_bf16 v[48:63], v[104:107], v[100:103], v[48:63]
	s_waitcnt lgkmcnt(0)
	v_mfma_f32_32x32x16_bf16 v[32:47], v[112:115], v[100:103], v[32:47]
	v_mfma_f32_32x32x16_bf16 v[16:31], v[104:107], v[108:111], v[16:31]
	v_mfma_f32_32x32x16_bf16 v[0:15], v[112:115], v[108:111], v[0:15]
	ds_read_b128 v[100:103], v86 offset:64
	ds_read_b128 v[104:107], v86 offset:4672
	ds_read_b128 v[108:111], v87 offset:18496
	ds_read_b128 v[112:115], v87 offset:23104
	s_waitcnt lgkmcnt(1)
	v_mfma_f32_32x32x16_bf16 v[48:63], v[108:111], v[100:103], v[48:63]
	s_waitcnt lgkmcnt(0)
	v_mfma_f32_32x32x16_bf16 v[32:47], v[112:115], v[100:103], v[32:47]
	v_mfma_f32_32x32x16_bf16 v[16:31], v[108:111], v[104:107], v[16:31]
	v_mfma_f32_32x32x16_bf16 v[0:15], v[112:115], v[104:107], v[0:15]
	ds_read_b128 v[100:103], v86 offset:96
	ds_read_b128 v[104:107], v86 offset:4704
	ds_read_b128 v[108:111], v87 offset:18528
	ds_read_b128 v[112:115], v87 offset:23136
	s_waitcnt lgkmcnt(0)
	s_barrier
	v_mfma_f32_32x32x16_bf16 v[48:63], v[108:111], v[100:103], v[48:63]
	v_mfma_f32_32x32x16_bf16 v[32:47], v[112:115], v[100:103], v[32:47]
	v_mfma_f32_32x32x16_bf16 v[0:15], v[112:115], v[104:107], v[0:15]
	v_mfma_f32_32x32x16_bf16 v[16:31], v[108:111], v[104:107], v[16:31]
	s_nop 8
	ds_write_b128 v84, v[48:51]
	ds_write_b128 v84, v[52:55] offset:32
	ds_write_b128 v84, v[56:59] offset:64
	ds_write_b128 v84, v[60:63] offset:96
	ds_write_b128 v84, v[32:35] offset:128
	ds_write_b128 v84, v[36:39] offset:160
	ds_write_b128 v84, v[40:43] offset:192
	ds_write_b128 v84, v[44:47] offset:224
	ds_write_b128 v84, v[16:19] offset:16896
	ds_write_b128 v84, v[20:23] offset:16928
	ds_write_b128 v84, v[24:27] offset:16960
	ds_write_b128 v84, v[28:31] offset:16992
	ds_write_b128 v84, v[0:3] offset:17024
	ds_write_b128 v84, v[4:7] offset:17056
	ds_write_b128 v84, v[8:11] offset:17088
	ds_write_b128 v84, v[12:15] offset:17120
	v_or_b32_e32 v0, s35, v80
	v_lshlrev_b32_e32 v64, 2, v0
	v_add_u32_e32 v1, s8, v88
	v_lshlrev_b32_e32 v0, 1, v0
	v_lshl_add_u64 v[8:9], s[80:81], 0, v[64:65]
	v_lshl_or_b32 v64, v1, 11, v0
	v_add_u32_e32 v1, s8, v90
	v_lshl_add_u64 v[10:11], s[6:7], 0, v[64:65]
	v_lshl_or_b32 v64, v1, 11, v0
	v_add_u32_e32 v1, s8, v92
	v_lshl_add_u64 v[12:13], s[6:7], 0, v[64:65]
	v_lshl_or_b32 v64, v1, 11, v0
	v_add_u32_e32 v1, s8, v165
	v_lshl_add_u64 v[14:15], s[6:7], 0, v[64:65]
	v_lshl_or_b32 v64, v1, 11, v0
	v_lshl_add_u64 v[16:17], s[6:7], 0, v[64:65]
	s_mov_b64 s[8:9], 0
	v_mov_b32_e32 v20, v94
	v_mov_b32_e32 v21, v93
	v_mov_b32_e32 v22, v91
	v_mov_b32_e32 v23, v89
	s_waitcnt lgkmcnt(0)
	s_barrier
	global_load_dwordx4 v[28:31], v[8:9], off
	s_waitcnt vmcnt(0)
.LBB0_952:
	s_nop 0
	ds_read_b128 v[0:3], v20
	v_lshl_add_u64 v[18:19], v[16:17], 0, s[8:9]
	v_add_u32_e32 v20, 0x4200, v20
	s_waitcnt lgkmcnt(0)
	v_add_f32_e32 v0, v0, v28
	v_mul_f32_e32 v0, 0xbfb8aa3b, v0
	v_exp_f32_e32 v0, v0
	v_add_f32_e32 v1, v1, v29
	v_mul_f32_e32 v1, 0xbfb8aa3b, v1
	v_exp_f32_e32 v1, v1
	v_add_f32_e32 v0, 1.0, v0
	v_div_scale_f32 v4, s[54:55], v0, v0, 1.0
	v_rcp_f32_e32 v24, v4
	v_add_f32_e32 v1, 1.0, v1
	v_add_f32_e32 v2, v2, v30
	v_mul_f32_e32 v2, 0xbfb8aa3b, v2
	v_fma_f32 v25, -v4, v24, 1.0
	v_fmac_f32_e32 v24, v25, v24
	v_div_scale_f32 v25, vcc, 1.0, v0, 1.0
	v_mul_f32_e32 v26, v25, v24
	v_fma_f32 v27, -v4, v26, v25
	v_fmac_f32_e32 v26, v27, v24
	v_fma_f32 v4, -v4, v26, v25
	v_div_fmas_f32 v4, v4, v24, v26
	v_div_fixup_f32 v0, v4, v0, 1.0
	v_div_scale_f32 v4, s[54:55], v1, v1, 1.0
	v_rcp_f32_e32 v5, v4
	v_exp_f32_e32 v2, v2
	v_add_f32_e32 v3, v3, v31
	v_mul_f32_e32 v3, 0xbfb8aa3b, v3
	v_fma_f32 v24, -v4, v5, 1.0
	v_fmac_f32_e32 v5, v24, v5
	v_div_scale_f32 v24, vcc, 1.0, v1, 1.0
	v_mul_f32_e32 v25, v24, v5
	v_fma_f32 v26, -v4, v25, v24
	v_fmac_f32_e32 v25, v26, v5
	v_fma_f32 v4, -v4, v25, v24
	v_div_fmas_f32 v4, v4, v5, v25
	v_add_f32_e32 v2, 1.0, v2
	v_div_fixup_f32 v1, v4, v1, 1.0
	v_div_scale_f32 v4, s[54:55], v2, v2, 1.0
	v_rcp_f32_e32 v5, v4
	v_exp_f32_e32 v3, v3
	v_cvt_pk_bf16_f32 v0, v0, v1
	v_fma_f32 v6, -v4, v5, 1.0
	v_fmac_f32_e32 v5, v6, v5
	v_div_scale_f32 v6, vcc, 1.0, v2, 1.0
	v_mul_f32_e32 v24, v6, v5
	v_fma_f32 v25, -v4, v24, v6
	v_fmac_f32_e32 v24, v25, v5
	v_fma_f32 v4, -v4, v24, v6
	v_div_fmas_f32 v4, v4, v5, v24
	v_add_f32_e32 v3, 1.0, v3
	v_div_fixup_f32 v2, v4, v2, 1.0
	v_div_scale_f32 v4, s[54:55], v3, v3, 1.0
	v_rcp_f32_e32 v5, v4
	s_nop 0
	v_fma_f32 v6, -v4, v5, 1.0
	v_fmac_f32_e32 v5, v6, v5
	v_div_scale_f32 v6, vcc, 1.0, v3, 1.0
	v_mul_f32_e32 v7, v6, v5
	v_fma_f32 v24, -v4, v7, v6
	v_fmac_f32_e32 v7, v24, v5
	v_fma_f32 v4, -v4, v7, v6
	v_div_fmas_f32 v4, v4, v5, v7
	v_div_fixup_f32 v3, v4, v3, 1.0
	v_cvt_pk_bf16_f32 v1, v2, v3
	global_store_dwordx2 v[18:19], v[0:1], off
	s_nop 0
	ds_read_b128 v[0:3], v21
	v_lshl_add_u64 v[18:19], v[14:15], 0, s[8:9]
	v_add_u32_e32 v21, 0x4200, v21
	s_waitcnt lgkmcnt(0)
	v_add_f32_e32 v0, v0, v28
	v_mul_f32_e32 v0, 0xbfb8aa3b, v0
	v_exp_f32_e32 v0, v0
	v_add_f32_e32 v1, v1, v29
	v_mul_f32_e32 v1, 0xbfb8aa3b, v1
	v_exp_f32_e32 v1, v1
	v_add_f32_e32 v0, 1.0, v0
	v_div_scale_f32 v4, s[54:55], v0, v0, 1.0
	v_rcp_f32_e32 v24, v4
	v_add_f32_e32 v1, 1.0, v1
	v_add_f32_e32 v2, v2, v30
	v_mul_f32_e32 v2, 0xbfb8aa3b, v2
	v_fma_f32 v25, -v4, v24, 1.0
	v_fmac_f32_e32 v24, v25, v24
	v_div_scale_f32 v25, vcc, 1.0, v0, 1.0
	v_mul_f32_e32 v26, v25, v24
	v_fma_f32 v27, -v4, v26, v25
	v_fmac_f32_e32 v26, v27, v24
	v_fma_f32 v4, -v4, v26, v25
	v_div_fmas_f32 v4, v4, v24, v26
	v_div_fixup_f32 v0, v4, v0, 1.0
	v_div_scale_f32 v4, s[54:55], v1, v1, 1.0
	v_rcp_f32_e32 v5, v4
	v_exp_f32_e32 v2, v2
	v_add_f32_e32 v3, v3, v31
	v_mul_f32_e32 v3, 0xbfb8aa3b, v3
	v_fma_f32 v24, -v4, v5, 1.0
	v_fmac_f32_e32 v5, v24, v5
	v_div_scale_f32 v24, vcc, 1.0, v1, 1.0
	v_mul_f32_e32 v25, v24, v5
	v_fma_f32 v26, -v4, v25, v24
	v_fmac_f32_e32 v25, v26, v5
	v_fma_f32 v4, -v4, v25, v24
	v_div_fmas_f32 v4, v4, v5, v25
	v_add_f32_e32 v2, 1.0, v2
	v_div_fixup_f32 v1, v4, v1, 1.0
	v_div_scale_f32 v4, s[54:55], v2, v2, 1.0
	v_rcp_f32_e32 v5, v4
	v_exp_f32_e32 v3, v3
	v_cvt_pk_bf16_f32 v0, v0, v1
	v_fma_f32 v6, -v4, v5, 1.0
	v_fmac_f32_e32 v5, v6, v5
	v_div_scale_f32 v6, vcc, 1.0, v2, 1.0
	v_mul_f32_e32 v24, v6, v5
	v_fma_f32 v25, -v4, v24, v6
	v_fmac_f32_e32 v24, v25, v5
	v_fma_f32 v4, -v4, v24, v6
	v_div_fmas_f32 v4, v4, v5, v24
	v_add_f32_e32 v3, 1.0, v3
	v_div_fixup_f32 v2, v4, v2, 1.0
	v_div_scale_f32 v4, s[54:55], v3, v3, 1.0
	v_rcp_f32_e32 v5, v4
	s_nop 0
	v_fma_f32 v6, -v4, v5, 1.0
	v_fmac_f32_e32 v5, v6, v5
	v_div_scale_f32 v6, vcc, 1.0, v3, 1.0
	v_mul_f32_e32 v7, v6, v5
	v_fma_f32 v24, -v4, v7, v6
	v_fmac_f32_e32 v7, v24, v5
	v_fma_f32 v4, -v4, v7, v6
	v_div_fmas_f32 v4, v4, v5, v7
	v_div_fixup_f32 v3, v4, v3, 1.0
	v_cvt_pk_bf16_f32 v1, v2, v3
	global_store_dwordx2 v[18:19], v[0:1], off
	s_nop 0
	ds_read_b128 v[0:3], v22
	v_lshl_add_u64 v[18:19], v[12:13], 0, s[8:9]
	v_add_u32_e32 v22, 0x4200, v22
	s_waitcnt lgkmcnt(0)
	v_add_f32_e32 v0, v0, v28
	v_mul_f32_e32 v0, 0xbfb8aa3b, v0
	v_exp_f32_e32 v0, v0
	v_add_f32_e32 v1, v1, v29
	v_mul_f32_e32 v1, 0xbfb8aa3b, v1
	v_exp_f32_e32 v1, v1
	v_add_f32_e32 v0, 1.0, v0
	v_div_scale_f32 v4, s[54:55], v0, v0, 1.0
	v_rcp_f32_e32 v24, v4
	v_add_f32_e32 v1, 1.0, v1
	v_add_f32_e32 v2, v2, v30
	v_mul_f32_e32 v2, 0xbfb8aa3b, v2
	v_fma_f32 v25, -v4, v24, 1.0
	v_fmac_f32_e32 v24, v25, v24
	v_div_scale_f32 v25, vcc, 1.0, v0, 1.0
	v_mul_f32_e32 v26, v25, v24
	v_fma_f32 v27, -v4, v26, v25
	v_fmac_f32_e32 v26, v27, v24
	v_fma_f32 v4, -v4, v26, v25
	v_div_fmas_f32 v4, v4, v24, v26
	v_div_fixup_f32 v0, v4, v0, 1.0
	v_div_scale_f32 v4, s[54:55], v1, v1, 1.0
	v_rcp_f32_e32 v5, v4
	v_exp_f32_e32 v2, v2
	v_add_f32_e32 v3, v3, v31
	v_mul_f32_e32 v3, 0xbfb8aa3b, v3
	v_fma_f32 v24, -v4, v5, 1.0
	v_fmac_f32_e32 v5, v24, v5
	v_div_scale_f32 v24, vcc, 1.0, v1, 1.0
	v_mul_f32_e32 v25, v24, v5
	v_fma_f32 v26, -v4, v25, v24
	v_fmac_f32_e32 v25, v26, v5
	v_fma_f32 v4, -v4, v25, v24
	v_div_fmas_f32 v4, v4, v5, v25
	v_add_f32_e32 v2, 1.0, v2
	v_div_fixup_f32 v1, v4, v1, 1.0
	v_div_scale_f32 v4, s[54:55], v2, v2, 1.0
	v_rcp_f32_e32 v5, v4
	v_exp_f32_e32 v3, v3
	v_cvt_pk_bf16_f32 v0, v0, v1
	v_fma_f32 v6, -v4, v5, 1.0
	v_fmac_f32_e32 v5, v6, v5
	v_div_scale_f32 v6, vcc, 1.0, v2, 1.0
	v_mul_f32_e32 v24, v6, v5
	v_fma_f32 v25, -v4, v24, v6
	v_fmac_f32_e32 v24, v25, v5
	v_fma_f32 v4, -v4, v24, v6
	v_div_fmas_f32 v4, v4, v5, v24
	v_add_f32_e32 v3, 1.0, v3
	v_div_fixup_f32 v2, v4, v2, 1.0
	v_div_scale_f32 v4, s[54:55], v3, v3, 1.0
	v_rcp_f32_e32 v5, v4
	s_nop 0
	v_fma_f32 v6, -v4, v5, 1.0
	v_fmac_f32_e32 v5, v6, v5
	v_div_scale_f32 v6, vcc, 1.0, v3, 1.0
	v_mul_f32_e32 v7, v6, v5
	v_fma_f32 v24, -v4, v7, v6
	v_fmac_f32_e32 v7, v24, v5
	v_fma_f32 v4, -v4, v7, v6
	v_div_fmas_f32 v4, v4, v5, v7
	v_div_fixup_f32 v3, v4, v3, 1.0
	v_cvt_pk_bf16_f32 v1, v2, v3
	global_store_dwordx2 v[18:19], v[0:1], off
	s_nop 0
	ds_read_b128 v[0:3], v23
	v_lshl_add_u64 v[18:19], v[10:11], 0, s[8:9]
	s_add_u32 s8, s8, 0x10000
	s_addc_u32 s9, s9, 0
	v_add_u32_e32 v23, 0x4200, v23
	s_cmp_eq_u32 s8, 0x40000
	s_waitcnt lgkmcnt(0)
	v_add_f32_e32 v0, v0, v28
	v_mul_f32_e32 v0, 0xbfb8aa3b, v0
	v_exp_f32_e32 v0, v0
	v_add_f32_e32 v1, v1, v29
	v_mul_f32_e32 v1, 0xbfb8aa3b, v1
	v_exp_f32_e32 v1, v1
	v_add_f32_e32 v0, 1.0, v0
	v_div_scale_f32 v4, s[54:55], v0, v0, 1.0
	v_rcp_f32_e32 v24, v4
	v_add_f32_e32 v1, 1.0, v1
	v_add_f32_e32 v2, v2, v30
	v_mul_f32_e32 v2, 0xbfb8aa3b, v2
	v_fma_f32 v25, -v4, v24, 1.0
	v_fmac_f32_e32 v24, v25, v24
	v_div_scale_f32 v25, vcc, 1.0, v0, 1.0
	v_mul_f32_e32 v26, v25, v24
	v_fma_f32 v27, -v4, v26, v25
	v_fmac_f32_e32 v26, v27, v24
	v_fma_f32 v4, -v4, v26, v25
	v_div_fmas_f32 v4, v4, v24, v26
	v_div_fixup_f32 v0, v4, v0, 1.0
	v_div_scale_f32 v4, s[54:55], v1, v1, 1.0
	v_rcp_f32_e32 v5, v4
	v_exp_f32_e32 v2, v2
	v_add_f32_e32 v3, v3, v31
	v_mul_f32_e32 v3, 0xbfb8aa3b, v3
	v_fma_f32 v24, -v4, v5, 1.0
	v_fmac_f32_e32 v5, v24, v5
	v_div_scale_f32 v24, vcc, 1.0, v1, 1.0
	v_mul_f32_e32 v25, v24, v5
	v_fma_f32 v26, -v4, v25, v24
	v_fmac_f32_e32 v25, v26, v5
	v_fma_f32 v4, -v4, v25, v24
	v_div_fmas_f32 v4, v4, v5, v25
	v_add_f32_e32 v2, 1.0, v2
	v_div_fixup_f32 v1, v4, v1, 1.0
	v_div_scale_f32 v4, s[54:55], v2, v2, 1.0
	v_rcp_f32_e32 v5, v4
	v_exp_f32_e32 v3, v3
	v_cvt_pk_bf16_f32 v0, v0, v1
	v_fma_f32 v6, -v4, v5, 1.0
	v_fmac_f32_e32 v5, v6, v5
	v_div_scale_f32 v6, vcc, 1.0, v2, 1.0
	v_mul_f32_e32 v24, v6, v5
	v_fma_f32 v25, -v4, v24, v6
	v_fmac_f32_e32 v24, v25, v5
	v_fma_f32 v4, -v4, v24, v6
	v_div_fmas_f32 v4, v4, v5, v24
	v_add_f32_e32 v3, 1.0, v3
	v_div_fixup_f32 v2, v4, v2, 1.0
	v_div_scale_f32 v4, s[54:55], v3, v3, 1.0
	v_rcp_f32_e32 v5, v4
	s_nop 0
	v_fma_f32 v6, -v4, v5, 1.0
	v_fmac_f32_e32 v5, v6, v5
	v_div_scale_f32 v6, vcc, 1.0, v3, 1.0
	v_mul_f32_e32 v7, v6, v5
	v_fma_f32 v24, -v4, v7, v6
	v_fmac_f32_e32 v7, v24, v5
	v_fma_f32 v4, -v4, v7, v6
	v_div_fmas_f32 v4, v4, v5, v7
	v_div_fixup_f32 v3, v4, v3, 1.0
	v_cvt_pk_bf16_f32 v1, v2, v3
	global_store_dwordx2 v[18:19], v[0:1], off
	s_cbranch_scc0 .LBB0_952

.LBB0_955:
	v_lshlrev_b32_e32 v1, 7, v157
	v_or_b32_e32 v0, s28, v157
	v_lshl_or_b32 v64, s29, 14, v1
	v_lshl_add_u64 v[16:17], v[74:75], 0, v[64:65]
	v_lshlrev_b32_e32 v64, 7, v0
	v_lshl_add_u64 v[28:29], v[76:77], 0, v[64:65]
	v_add_co_u32_e32 v8, vcc, 0x3000, v28
	s_nop 1
	v_addc_co_u32_e32 v9, vcc, 0, v29, vcc
	v_add_co_u32_e32 v4, vcc, s20, v16
	s_nop 1
	v_addc_co_u32_e32 v5, vcc, 0, v17, vcc
	v_add_co_u32_e32 v12, vcc, s21, v16
	global_load_dwordx4 v[0:3], v[4:5], off offset:-4096
	s_nop 0
	global_load_dwordx4 v[4:7], v[4:5], off
	v_addc_co_u32_e32 v13, vcc, 0, v17, vcc
	global_load_dwordx4 v[8:11], v[8:9], off
	s_nop 0
	global_load_dwordx4 v[12:15], v[12:13], off
	s_nop 0
	global_load_dwordx4 v[16:19], v[16:17], off
	s_nop 0
	global_load_dwordx4 v[20:23], v[28:29], off
	v_add_co_u32_e32 v24, vcc, s19, v28
	s_nop 1
	v_addc_co_u32_e32 v25, vcc, 0, v29, vcc
	global_load_dwordx4 v[24:27], v[24:25], off
	v_add_co_u32_e32 v28, vcc, s20, v28
	s_nop 1
	v_addc_co_u32_e32 v29, vcc, 0, v29, vcc
	global_load_dwordx4 v[28:31], v[28:29], off
	s_barrier
	s_waitcnt vmcnt(3)
	ds_write_b128 v85, v[16:19]
	s_waitcnt vmcnt(2)
	ds_write_b128 v85, v[20:23] offset:18432
	s_waitcnt vmcnt(1)
	ds_write_b128 v85, v[24:27] offset:23040
	ds_write_b128 v85, v[8:11] offset:32256
	ds_write_b128 v85, v[0:3] offset:4608
	ds_write_b128 v85, v[4:7] offset:9216
	ds_write_b128 v85, v[12:15] offset:13824
	s_waitcnt vmcnt(0)
	ds_write_b128 v85, v[28:31] offset:27648
	s_waitcnt lgkmcnt(0)
	s_barrier
	ds_read_b128 v[0:3], v87 offset:18432
	ds_read_b128 v[4:7], v86
	ds_read_b128 v[100:103], v86 offset:32
	ds_read_b128 v[104:107], v87 offset:18464
	ds_read_b128 v[8:11], v87 offset:23040
	ds_read_b128 v[108:111], v87 offset:23072
	s_lshl_b32 s8, s16, 10
	s_waitcnt lgkmcnt(4)
	v_mfma_f32_32x32x16_bf16 v[48:63], v[0:3], v[4:7], 0
	v_or_b32_e32 v64, s28, v80
	v_readlane_b32 s72, v253, 42
	s_or_b32 s8, s17, s8
	v_readlane_b32 s74, v253, 44
	v_readlane_b32 s75, v253, 45
	v_readlane_b32 s73, v253, 43
	v_readlane_b32 s76, v253, 46
	s_waitcnt lgkmcnt(1)
	v_mfma_f32_32x32x16_bf16 v[32:47], v[8:11], v[4:7], 0
	ds_read_b128 v[4:7], v86 offset:4608
	ds_read_b128 v[112:115], v86 offset:4640
	v_readlane_b32 s77, v253, 47
	v_readlane_b32 s78, v253, 48
	v_readlane_b32 s79, v253, 49
	v_readlane_b32 s80, v253, 50
	v_readlane_b32 s81, v253, 51
	v_readlane_b32 s82, v253, 52
	s_waitcnt lgkmcnt(1)
	v_mfma_f32_32x32x16_bf16 v[16:31], v[0:3], v[4:7], 0
	v_readlane_b32 s83, v253, 53
	v_readlane_b32 s84, v253, 54
	v_readlane_b32 s85, v253, 55
	v_readlane_b32 s86, v253, 56
	v_readlane_b32 s87, v253, 57
	v_mfma_f32_32x32x16_bf16 v[0:15], v[8:11], v[4:7], 0
	v_mfma_f32_32x32x16_bf16 v[48:63], v[104:107], v[100:103], v[48:63]
	v_mfma_f32_32x32x16_bf16 v[32:47], v[108:111], v[100:103], v[32:47]
	s_waitcnt lgkmcnt(0)
	v_mfma_f32_32x32x16_bf16 v[16:31], v[104:107], v[112:115], v[16:31]
	v_mfma_f32_32x32x16_bf16 v[0:15], v[108:111], v[112:115], v[0:15]
	ds_read_b128 v[100:103], v87 offset:18496
	ds_read_b128 v[104:107], v86 offset:64
	ds_read_b128 v[108:111], v86 offset:96
	ds_read_b128 v[112:115], v87 offset:18528
	ds_read_b128 v[116:119], v87 offset:23104
	ds_read_b128 v[120:123], v87 offset:23136
	s_waitcnt lgkmcnt(4)
	v_mfma_f32_32x32x16_bf16 v[48:63], v[100:103], v[104:107], v[48:63]
	s_waitcnt lgkmcnt(1)
	v_mfma_f32_32x32x16_bf16 v[32:47], v[116:119], v[104:107], v[32:47]
	ds_read_b128 v[104:107], v86 offset:4672
	ds_read_b128 v[124:127], v86 offset:4704
	s_waitcnt lgkmcnt(0)
	s_barrier
	v_mfma_f32_32x32x16_bf16 v[0:15], v[116:119], v[104:107], v[0:15]
	v_mfma_f32_32x32x16_bf16 v[16:31], v[100:103], v[104:107], v[16:31]
	v_mfma_f32_32x32x16_bf16 v[48:63], v[112:115], v[108:111], v[48:63]
	v_mfma_f32_32x32x16_bf16 v[32:47], v[120:123], v[108:111], v[32:47]
	s_nop 10
	ds_write_b128 v84, v[48:51]
	ds_write_b128 v84, v[52:55] offset:32
	ds_write_b128 v84, v[56:59] offset:64
	ds_write_b128 v84, v[60:63] offset:96
	ds_write_b128 v84, v[32:35] offset:128
	v_mfma_f32_32x32x16_bf16 v[0:15], v[120:123], v[124:127], v[0:15]
	v_mfma_f32_32x32x16_bf16 v[16:31], v[112:115], v[124:127], v[16:31]
	ds_write_b128 v84, v[36:39] offset:160
	ds_write_b128 v84, v[40:43] offset:192
	ds_write_b128 v84, v[44:47] offset:224
	s_nop 8
	ds_write_b128 v84, v[16:19] offset:16896
	ds_write_b128 v84, v[20:23] offset:16928
	ds_write_b128 v84, v[24:27] offset:16960
	ds_write_b128 v84, v[28:31] offset:16992
	ds_write_b128 v84, v[0:3] offset:17024
	ds_write_b128 v84, v[4:7] offset:17056
	ds_write_b128 v84, v[8:11] offset:17088
	ds_write_b128 v84, v[12:15] offset:17120
	v_add_lshl_u32 v0, s8, v88, 11
	v_mov_b32_e32 v1, v65
	v_lshlrev_b64 v[2:3], 1, v[64:65]
	v_lshl_add_u64 v[8:9], v[64:65], 2, s[74:75]
	v_lshl_add_u64 v[0:1], v[0:1], 0, v[2:3]
	v_add_lshl_u32 v64, s8, v90, 11
	v_lshl_add_u64 v[10:11], s[2:3], 0, v[0:1]
	v_lshl_add_u64 v[0:1], v[64:65], 0, v[2:3]
	v_add_lshl_u32 v64, s8, v92, 11
	v_lshl_add_u64 v[12:13], s[2:3], 0, v[0:1]
	v_lshl_add_u64 v[0:1], v[64:65], 0, v[2:3]
	v_add_lshl_u32 v64, s8, v165, 11
	v_lshl_add_u64 v[14:15], s[2:3], 0, v[0:1]
	v_lshl_add_u64 v[0:1], v[64:65], 0, v[2:3]
	v_lshl_add_u64 v[16:17], s[2:3], 0, v[0:1]
	s_mov_b64 s[8:9], 0
	v_mov_b32_e32 v18, v94
	v_mov_b32_e32 v19, v93
	v_mov_b32_e32 v20, v91
	v_mov_b32_e32 v21, v89
	s_waitcnt lgkmcnt(0)
	s_barrier
	global_load_dwordx4 v[28:31], v[8:9], off
	s_mov_b32 s16, 0xbf60028b
	s_waitcnt vmcnt(0)
.Ldecay_loop:
	ds_read_b128 v[0:3], v18
	ds_read_b128 v[4:7], v19
	ds_read_b128 v[22:25], v20
	ds_read_b128 v[32:35], v21
	s_waitcnt lgkmcnt(3)
	v_add_f32_e32 v0, v0, v28
	v_add_f32_e32 v1, v1, v29
	v_add_f32_e32 v2, v2, v30
	v_add_f32_e32 v3, v3, v31
	v_mul_f32_e32 v0, 0xbfb8aa3b, v0
	v_mul_f32_e32 v1, 0xbfb8aa3b, v1
	v_mul_f32_e32 v2, 0xbfb8aa3b, v2
	v_mul_f32_e32 v3, 0xbfb8aa3b, v3
	v_exp_f32_e32 v0, v0
	v_exp_f32_e32 v1, v1
	v_exp_f32_e32 v2, v2
	v_exp_f32_e32 v3, v3
	v_add_f32_e32 v0, 1.0, v0
	v_add_f32_e32 v1, 1.0, v1
	v_add_f32_e32 v2, 1.0, v2
	v_add_f32_e32 v3, 1.0, v3
	v_rcp_f32_e32 v0, v0
	v_rcp_f32_e32 v1, v1
	v_rcp_f32_e32 v2, v2
	v_rcp_f32_e32 v3, v3
	v_mul_f32_e32 v0, s16, v0
	v_mul_f32_e32 v1, s16, v1
	v_mul_f32_e32 v2, s16, v2
	v_mul_f32_e32 v3, s16, v3
	v_exp_f32_e32 v0, v0
	v_exp_f32_e32 v1, v1
	v_exp_f32_e32 v2, v2
	v_exp_f32_e32 v3, v3
	v_cvt_f16_f32_e32 v0, v0
	v_cvt_f16_f32_sdwa v1, v1 dst_sel:WORD_1 dst_unused:UNUSED_PAD src0_sel:DWORD
	v_cvt_f16_f32_e32 v2, v2
	v_cvt_f16_f32_sdwa v3, v3 dst_sel:WORD_1 dst_unused:UNUSED_PAD src0_sel:DWORD
	v_lshl_add_u64 v[26:27], v[16:17], 0, s[8:9]
	v_or_b32_e32 v0, v1, v0
	v_or_b32_e32 v1, v3, v2
	global_store_dwordx2 v[26:27], v[0:1], off
	s_waitcnt lgkmcnt(2)
	v_add_f32_e32 v4, v4, v28
	v_add_f32_e32 v5, v5, v29
	v_add_f32_e32 v6, v6, v30
	v_add_f32_e32 v7, v7, v31
	v_mul_f32_e32 v4, 0xbfb8aa3b, v4
	v_mul_f32_e32 v5, 0xbfb8aa3b, v5
	v_mul_f32_e32 v6, 0xbfb8aa3b, v6
	v_mul_f32_e32 v7, 0xbfb8aa3b, v7
	v_exp_f32_e32 v4, v4
	v_exp_f32_e32 v5, v5
	v_exp_f32_e32 v6, v6
	v_exp_f32_e32 v7, v7
	v_add_f32_e32 v4, 1.0, v4
	v_add_f32_e32 v5, 1.0, v5
	v_add_f32_e32 v6, 1.0, v6
	v_add_f32_e32 v7, 1.0, v7
	v_rcp_f32_e32 v4, v4
	v_rcp_f32_e32 v5, v5
	v_rcp_f32_e32 v6, v6
	v_rcp_f32_e32 v7, v7
	v_mul_f32_e32 v4, s16, v4
	v_mul_f32_e32 v5, s16, v5
	v_mul_f32_e32 v6, s16, v6
	v_mul_f32_e32 v7, s16, v7
	v_exp_f32_e32 v4, v4
	v_exp_f32_e32 v5, v5
	v_exp_f32_e32 v6, v6
	v_exp_f32_e32 v7, v7
	v_cvt_f16_f32_e32 v4, v4
	v_cvt_f16_f32_sdwa v5, v5 dst_sel:WORD_1 dst_unused:UNUSED_PAD src0_sel:DWORD
	v_cvt_f16_f32_e32 v6, v6
	v_cvt_f16_f32_sdwa v7, v7 dst_sel:WORD_1 dst_unused:UNUSED_PAD src0_sel:DWORD
	v_lshl_add_u64 v[26:27], v[14:15], 0, s[8:9]
	v_or_b32_e32 v4, v5, v4
	v_or_b32_e32 v5, v7, v6
	global_store_dwordx2 v[26:27], v[4:5], off
	s_waitcnt lgkmcnt(1)
	v_add_f32_e32 v22, v22, v28
	v_add_f32_e32 v23, v23, v29
	v_add_f32_e32 v24, v24, v30
	v_add_f32_e32 v25, v25, v31
	v_mul_f32_e32 v22, 0xbfb8aa3b, v22
	v_mul_f32_e32 v23, 0xbfb8aa3b, v23
	v_mul_f32_e32 v24, 0xbfb8aa3b, v24
	v_mul_f32_e32 v25, 0xbfb8aa3b, v25
	v_exp_f32_e32 v22, v22
	v_exp_f32_e32 v23, v23
	v_exp_f32_e32 v24, v24
	v_exp_f32_e32 v25, v25
	v_add_f32_e32 v22, 1.0, v22
	v_add_f32_e32 v23, 1.0, v23
	v_add_f32_e32 v24, 1.0, v24
	v_add_f32_e32 v25, 1.0, v25
	v_rcp_f32_e32 v22, v22
	v_rcp_f32_e32 v23, v23
	v_rcp_f32_e32 v24, v24
	v_rcp_f32_e32 v25, v25
	v_mul_f32_e32 v22, s16, v22
	v_mul_f32_e32 v23, s16, v23
	v_mul_f32_e32 v24, s16, v24
	v_mul_f32_e32 v25, s16, v25
	v_exp_f32_e32 v22, v22
	v_exp_f32_e32 v23, v23
	v_exp_f32_e32 v24, v24
	v_exp_f32_e32 v25, v25
	v_cvt_f16_f32_e32 v22, v22
	v_cvt_f16_f32_sdwa v23, v23 dst_sel:WORD_1 dst_unused:UNUSED_PAD src0_sel:DWORD
	v_cvt_f16_f32_e32 v24, v24
	v_cvt_f16_f32_sdwa v25, v25 dst_sel:WORD_1 dst_unused:UNUSED_PAD src0_sel:DWORD
	v_lshl_add_u64 v[26:27], v[12:13], 0, s[8:9]
	v_or_b32_e32 v22, v23, v22
	v_or_b32_e32 v23, v25, v24
	global_store_dwordx2 v[26:27], v[22:23], off
	s_waitcnt lgkmcnt(0)
	v_add_f32_e32 v32, v32, v28
	v_add_f32_e32 v33, v33, v29
	v_add_f32_e32 v34, v34, v30
	v_add_f32_e32 v35, v35, v31
	v_mul_f32_e32 v32, 0xbfb8aa3b, v32
	v_mul_f32_e32 v33, 0xbfb8aa3b, v33
	v_mul_f32_e32 v34, 0xbfb8aa3b, v34
	v_mul_f32_e32 v35, 0xbfb8aa3b, v35
	v_exp_f32_e32 v32, v32
	v_exp_f32_e32 v33, v33
	v_exp_f32_e32 v34, v34
	v_exp_f32_e32 v35, v35
	v_add_f32_e32 v32, 1.0, v32
	v_add_f32_e32 v33, 1.0, v33
	v_add_f32_e32 v34, 1.0, v34
	v_add_f32_e32 v35, 1.0, v35
	v_rcp_f32_e32 v32, v32
	v_rcp_f32_e32 v33, v33
	v_rcp_f32_e32 v34, v34
	v_rcp_f32_e32 v35, v35
	v_mul_f32_e32 v32, s16, v32
	v_mul_f32_e32 v33, s16, v33
	v_mul_f32_e32 v34, s16, v34
	v_mul_f32_e32 v35, s16, v35
	v_exp_f32_e32 v32, v32
	v_exp_f32_e32 v33, v33
	v_exp_f32_e32 v34, v34
	v_exp_f32_e32 v35, v35
	v_cvt_f16_f32_e32 v32, v32
	v_cvt_f16_f32_sdwa v33, v33 dst_sel:WORD_1 dst_unused:UNUSED_PAD src0_sel:DWORD
	v_cvt_f16_f32_e32 v34, v34
	v_cvt_f16_f32_sdwa v35, v35 dst_sel:WORD_1 dst_unused:UNUSED_PAD src0_sel:DWORD
	v_lshl_add_u64 v[26:27], v[10:11], 0, s[8:9]
	v_or_b32_e32 v32, v33, v32
	v_or_b32_e32 v33, v35, v34
	global_store_dwordx2 v[26:27], v[32:33], off
	s_add_u32 s8, s8, 0x10000
	s_addc_u32 s9, s9, 0
	v_add_u32_e32 v18, 0x4200, v18
	v_add_u32_e32 v19, 0x4200, v19
	v_add_u32_e32 v20, 0x4200, v20
	v_add_u32_e32 v21, 0x4200, v21
	s_cmp_eq_u32 s8, 0x40000
	s_cbranch_scc0 .Ldecay_loop
	s_branch .LBB0_943
